# per-XCD barrier: L1 invalidate (buffer_inv sc1) issued before the arrival poll instead of after it, so it overlaps the wait for the other workgroups
# speedup vs baseline: 1.0084x; 1.0084x over previous
; __device__ __forceinline__ void xcd_local_bar(unsigned* ctr, unsigned target, bool leader) {
;     asm volatile("s_waitcnt vmcnt(0) lgkmcnt(0)" ::: "memory");
;     __syncthreads();
;     if (leader) {
;         __hip_atomic_fetch_add(ctr, 1u, __ATOMIC_RELAXED, __HIP_MEMORY_SCOPE_AGENT);
;         while (__hip_atomic_load(ctr, __ATOMIC_RELAXED, __HIP_MEMORY_SCOPE_AGENT) < target) __builtin_amdgcn_s_sleep(1);
;         __builtin_amdgcn_fence(__ATOMIC_ACQUIRE, "agent");
;         asm volatile("s_waitcnt vmcnt(0)" ::: "memory");
;     }
;     __syncthreads();
; }
.LBB0_355:
	s_or_b64 exec, exec, s[26:27]
	buffer_inv sc1
	v_mov_b32_e32 v0, 0
	global_load_dword v1, v0, s[10:11] offset:256 sc1
	s_waitcnt vmcnt(0)
	v_cmp_le_u32_e32 vcc, s54, v1
	s_cbranch_vccnz .LBB0_357
.LBB0_356:
	s_sleep 1
	global_load_dword v1, v0, s[10:11] offset:256 sc1
	s_waitcnt vmcnt(0)
	v_cmp_gt_u32_e32 vcc, s54, v1
	s_cbranch_vccnz .LBB0_356
.LBB0_357:
	s_waitcnt vmcnt(0)
.LBB0_358:
	s_or_b64 exec, exec, s[8:9]
	s_barrier
	s_mov_b32 s59, s54
	s_branch .LBB0_370

; __device__ __forceinline__ void xcd_local_bar(unsigned* ctr, unsigned target, bool leader) {
;     asm volatile("s_waitcnt vmcnt(0) lgkmcnt(0)" ::: "memory");
;     __syncthreads();
;     if (leader) {
;         __hip_atomic_fetch_add(ctr, 1u, __ATOMIC_RELAXED, __HIP_MEMORY_SCOPE_AGENT);
;         while (__hip_atomic_load(ctr, __ATOMIC_RELAXED, __HIP_MEMORY_SCOPE_AGENT) < target) __builtin_amdgcn_s_sleep(1);
;         __builtin_amdgcn_fence(__ATOMIC_ACQUIRE, "agent");
;         asm volatile("s_waitcnt vmcnt(0)" ::: "memory");
;     }
;     __syncthreads();
; }
.LBB0_484:
	s_or_b64 exec, exec, s[26:27]
	buffer_inv sc1
	v_mov_b32_e32 v0, 0
	global_load_dword v1, v0, s[10:11] offset:256 sc1
	s_waitcnt vmcnt(0)
	v_cmp_le_u32_e32 vcc, s24, v1
	s_cbranch_vccnz .LBB0_486
.LBB0_485:
	s_sleep 1
	global_load_dword v1, v0, s[10:11] offset:256 sc1
	s_waitcnt vmcnt(0)
	v_cmp_gt_u32_e32 vcc, s24, v1
	s_cbranch_vccnz .LBB0_485
.LBB0_486:
	s_waitcnt vmcnt(0)
.LBB0_487:
	s_or_b64 exec, exec, s[8:9]
	s_barrier
	s_branch .LBB0_498

; __device__ __forceinline__ void xcd_local_bar(unsigned* ctr, unsigned target, bool leader) {
;     asm volatile("s_waitcnt vmcnt(0) lgkmcnt(0)" ::: "memory");
;     __syncthreads();
;     if (leader) {
;         __hip_atomic_fetch_add(ctr, 1u, __ATOMIC_RELAXED, __HIP_MEMORY_SCOPE_AGENT);
;         while (__hip_atomic_load(ctr, __ATOMIC_RELAXED, __HIP_MEMORY_SCOPE_AGENT) < target) __builtin_amdgcn_s_sleep(1);
;         __builtin_amdgcn_fence(__ATOMIC_ACQUIRE, "agent");
;         asm volatile("s_waitcnt vmcnt(0)" ::: "memory");
;     }
;     __syncthreads();
; }
.LBB0_527:
	s_or_b64 exec, exec, s[28:29]
	buffer_inv sc1
	v_mov_b32_e32 v0, 0
	global_load_dword v1, v0, s[12:13] offset:256 sc1
	s_waitcnt vmcnt(0)
	v_cmp_le_u32_e32 vcc, s24, v1
	s_cbranch_vccnz .LBB0_529
.LBB0_528:
	s_sleep 1
	global_load_dword v1, v0, s[12:13] offset:256 sc1
	s_waitcnt vmcnt(0)
	v_cmp_gt_u32_e32 vcc, s24, v1
	s_cbranch_vccnz .LBB0_528
.LBB0_529:
	s_waitcnt vmcnt(0)
.LBB0_530:
	s_or_b64 exec, exec, s[10:11]
	s_barrier
	s_branch .LBB0_541

; __device__ __forceinline__ void xcd_local_bar(unsigned* ctr, unsigned target, bool leader) {
;     asm volatile("s_waitcnt vmcnt(0) lgkmcnt(0)" ::: "memory");
;     __syncthreads();
;     if (leader) {
;         __hip_atomic_fetch_add(ctr, 1u, __ATOMIC_RELAXED, __HIP_MEMORY_SCOPE_AGENT);
;         while (__hip_atomic_load(ctr, __ATOMIC_RELAXED, __HIP_MEMORY_SCOPE_AGENT) < target) __builtin_amdgcn_s_sleep(1);
;         __builtin_amdgcn_fence(__ATOMIC_ACQUIRE, "agent");
;         asm volatile("s_waitcnt vmcnt(0)" ::: "memory");
;     }
;     __syncthreads();
; }
.LBB0_586:
	s_or_b64 exec, exec, s[28:29]
	buffer_inv sc1
	v_mov_b32_e32 v0, 0
	global_load_dword v1, v0, s[14:15] offset:256 sc1
	s_waitcnt vmcnt(0)
	v_cmp_le_u32_e32 vcc, s24, v1
	s_cbranch_vccnz .LBB0_588
.LBB0_587:
	s_sleep 1
	global_load_dword v1, v0, s[14:15] offset:256 sc1
	s_waitcnt vmcnt(0)
	v_cmp_gt_u32_e32 vcc, s24, v1
	s_cbranch_vccnz .LBB0_587
.LBB0_588:
	s_waitcnt vmcnt(0)
.LBB0_589:
	s_or_b64 exec, exec, s[12:13]
	s_barrier
	s_branch .LBB0_600

; __device__ __forceinline__ void xcd_local_bar(unsigned* ctr, unsigned target, bool leader) {
;     asm volatile("s_waitcnt vmcnt(0) lgkmcnt(0)" ::: "memory");
;     __syncthreads();
;     if (leader) {
;         __hip_atomic_fetch_add(ctr, 1u, __ATOMIC_RELAXED, __HIP_MEMORY_SCOPE_AGENT);
;         while (__hip_atomic_load(ctr, __ATOMIC_RELAXED, __HIP_MEMORY_SCOPE_AGENT) < target) __builtin_amdgcn_s_sleep(1);
;         __builtin_amdgcn_fence(__ATOMIC_ACQUIRE, "agent");
;         asm volatile("s_waitcnt vmcnt(0)" ::: "memory");
;     }
;     __syncthreads();
; }
.LBB0_628:
	s_sleep 1
	global_load_dword v1, v0, s[14:15] offset:256 sc1
	s_waitcnt vmcnt(0)
	v_cmp_gt_u32_e32 vcc, s24, v1
	s_cbranch_vccnz .LBB0_628
.LBB0_629:
	s_waitcnt vmcnt(0)
.LBB0_630:
	s_or_b64 exec, exec, s[12:13]
	s_barrier
	s_branch .LBB0_641

; __device__ __forceinline__ void xcd_local_bar(unsigned* ctr, unsigned target, bool leader) {
;     asm volatile("s_waitcnt vmcnt(0) lgkmcnt(0)" ::: "memory");
;     __syncthreads();
;     if (leader) {
;         __hip_atomic_fetch_add(ctr, 1u, __ATOMIC_RELAXED, __HIP_MEMORY_SCOPE_AGENT);
;         while (__hip_atomic_load(ctr, __ATOMIC_RELAXED, __HIP_MEMORY_SCOPE_AGENT) < target) __builtin_amdgcn_s_sleep(1);
;         __builtin_amdgcn_fence(__ATOMIC_ACQUIRE, "agent");
;         asm volatile("s_waitcnt vmcnt(0)" ::: "memory");
;     }
;     __syncthreads();
; }
.LBB0_668:
	s_sleep 1
	global_load_dword v1, v0, s[14:15] offset:256 sc1
	s_waitcnt vmcnt(0)
	v_cmp_gt_u32_e32 vcc, s24, v1
	s_cbranch_vccnz .LBB0_668
.LBB0_669:
	s_waitcnt vmcnt(0)
.LBB0_670:
	s_or_b64 exec, exec, s[12:13]
	s_barrier
	s_branch .LBB0_681

; __device__ __forceinline__ void xcd_local_bar(unsigned* ctr, unsigned target, bool leader) {
;     asm volatile("s_waitcnt vmcnt(0) lgkmcnt(0)" ::: "memory");
;     __syncthreads();
;     if (leader) {
;         __hip_atomic_fetch_add(ctr, 1u, __ATOMIC_RELAXED, __HIP_MEMORY_SCOPE_AGENT);
;         while (__hip_atomic_load(ctr, __ATOMIC_RELAXED, __HIP_MEMORY_SCOPE_AGENT) < target) __builtin_amdgcn_s_sleep(1);
;         __builtin_amdgcn_fence(__ATOMIC_ACQUIRE, "agent");
;         asm volatile("s_waitcnt vmcnt(0)" ::: "memory");
;     }
;     __syncthreads();
; }
.LBB0_691:
	s_sleep 1
	global_load_dword v1, v0, s[14:15] offset:256 sc1
	s_waitcnt vmcnt(0)
	v_cmp_gt_u32_e32 vcc, s24, v1
	s_cbranch_vccnz .LBB0_691
.LBB0_692:
	s_waitcnt vmcnt(0)
.LBB0_693:
	s_or_b64 exec, exec, s[12:13]
	s_barrier
	s_branch .LBB0_740

; __device__ __forceinline__ void xcd_local_bar(unsigned* ctr, unsigned target, bool leader) {
;     asm volatile("s_waitcnt vmcnt(0) lgkmcnt(0)" ::: "memory");
;     __syncthreads();
;     if (leader) {
;         __hip_atomic_fetch_add(ctr, 1u, __ATOMIC_RELAXED, __HIP_MEMORY_SCOPE_AGENT);
;         while (__hip_atomic_load(ctr, __ATOMIC_RELAXED, __HIP_MEMORY_SCOPE_AGENT) < target) __builtin_amdgcn_s_sleep(1);
;         __builtin_amdgcn_fence(__ATOMIC_ACQUIRE, "agent");
;         asm volatile("s_waitcnt vmcnt(0)" ::: "memory");
;     }
;     __syncthreads();
; }
.LBB0_764:
	s_sleep 1
	global_load_dword v1, v0, s[14:15] offset:256 sc1
	s_waitcnt vmcnt(0)
	v_cmp_gt_u32_e32 vcc, s24, v1
	s_cbranch_vccnz .LBB0_764
.LBB0_765:
	s_waitcnt vmcnt(0)
.LBB0_766:
	s_or_b64 exec, exec, s[12:13]
	s_barrier
	s_branch .LBB0_777

; __device__ __forceinline__ void xcd_local_bar(unsigned* ctr, unsigned target, bool leader) {
;     asm volatile("s_waitcnt vmcnt(0) lgkmcnt(0)" ::: "memory");
;     __syncthreads();
;     if (leader) {
;         __hip_atomic_fetch_add(ctr, 1u, __ATOMIC_RELAXED, __HIP_MEMORY_SCOPE_AGENT);
;         while (__hip_atomic_load(ctr, __ATOMIC_RELAXED, __HIP_MEMORY_SCOPE_AGENT) < target) __builtin_amdgcn_s_sleep(1);
;         __builtin_amdgcn_fence(__ATOMIC_ACQUIRE, "agent");
;         asm volatile("s_waitcnt vmcnt(0)" ::: "memory");
;     }
;     __syncthreads();
; }
.LBB0_786:
	s_or_b64 exec, exec, s[12:13]
	buffer_inv sc1
	v_mov_b32_e32 v0, 0
	global_load_dword v1, v0, s[8:9] offset:256 sc1
	s_add_i32 s3, s59, s54
	s_waitcnt vmcnt(0)
	v_cmp_le_u32_e32 vcc, s3, v1
	s_cbranch_vccnz .LBB0_788
.LBB0_787:
	s_sleep 1
	global_load_dword v1, v0, s[8:9] offset:256 sc1
	s_waitcnt vmcnt(0)
	v_cmp_gt_u32_e32 vcc, s3, v1
	s_cbranch_vccnz .LBB0_787
.LBB0_788:
	s_waitcnt vmcnt(0)
.LBB0_789:
	s_or_b64 exec, exec, s[6:7]
	s_barrier
	s_branch .LBB0_840
